# v4 + hand-written streaming layer-0 input modulation (ring of 5 row buffers per wave)
# baseline (speedup 1.0000x reference)
; __device__ void phase_modulate0(PP P, int wid) {
;     ...
;     for (size_t it = (size_t)blockIdx.x * NTHREADS + tidx; it < (size_t)MT * 128; it += (size_t)gridDim.x * NTHREADS) {
;         const int token = (int)(it >> 7), c8 = (int)(it & 127) * 8, seq = token >> 11;
;         float x[8], sh[8], sc[8], u[8];
;         load8f(xin_row(P, token) + c8, x);
;         const float* mrow = mod + (size_t)(0 * NSEQ + seq) * 6 * D;
;         load8f(mrow + c8, sh); load8f(mrow + D + c8, sc);
; #pragma unroll
;         for (int e = 0; e < 8; ++e) u[e] = x[e] * (1.f + sc[e]) + sh[e];
;         store_A(A, false, token, c8, u);
;     }
.LBB0_107:
	s_or_b64 exec, exec, s[10:11]
	s_cmp_lg_u32 s14, 0x100
	s_cbranch_scc1 .Lm0_orig
	v_mbcnt_lo_u32_b32 v0, -1, 0
	v_mbcnt_hi_u32_b32 v0, -1, v0
	s_load_dwordx4 s[16:19], s[80:81], 0x0
	s_waitcnt lgkmcnt(0)
	s_add_u32 s10, s6, 0xe660000
	s_addc_u32 s11, s7, 0
	s_add_u32 s12, s6, 0xe200000
	s_addc_u32 s13, s7, 0
	s_mul_i32 s20, s2, 0x140
	s_add_i32 s7, s20, 0x140
	s_lshr_b32 s0, s82, 6
	s_add_i32 s20, s20, s0
	s_mov_b32 s21, -1
	v_lshlrev_b32_e32 v1, 4, v0
	v_lshlrev_b32_e32 v6, 5, v0
	s_lshl_b32 s0, s20, 12
	s_sub_u32 s1, s0, 0x10000000
	s_cmp_lt_u32 s20, 0x10000
	s_cselect_b32 s0, s0, s1
	s_cselect_b32 s24, s16, s18
	s_cselect_b32 s25, s17, s19
	s_add_u32 s8, s24, s0
	s_addc_u32 s9, s25, 0
	global_load_dwordx4 v[40:43], v6, s[8:9]
	global_load_dwordx4 v[44:47], v6, s[8:9] offset:16
	global_load_dwordx4 v[48:51], v6, s[8:9] offset:2048
	global_load_dwordx4 v[52:55], v6, s[8:9] offset:2064
	s_add_i32 s22, s20, 8
	s_lshl_b32 s0, s22, 12
	s_sub_u32 s1, s0, 0x10000000
	s_cmp_lt_u32 s22, 0x10000
	s_cselect_b32 s0, s0, s1
	s_cselect_b32 s24, s16, s18
	s_cselect_b32 s25, s17, s19
	s_add_u32 s8, s24, s0
	s_addc_u32 s9, s25, 0
	global_load_dwordx4 v[56:59], v6, s[8:9]
	global_load_dwordx4 v[60:63], v6, s[8:9] offset:16
	global_load_dwordx4 v[64:67], v6, s[8:9] offset:2048
	global_load_dwordx4 v[68:71], v6, s[8:9] offset:2064
	s_add_i32 s22, s20, 16
	s_lshl_b32 s0, s22, 12
	s_sub_u32 s1, s0, 0x10000000
	s_cmp_lt_u32 s22, 0x10000
	s_cselect_b32 s0, s0, s1
	s_cselect_b32 s24, s16, s18
	s_cselect_b32 s25, s17, s19
	s_add_u32 s8, s24, s0
	s_addc_u32 s9, s25, 0
	global_load_dwordx4 v[72:75], v6, s[8:9]
	global_load_dwordx4 v[76:79], v6, s[8:9] offset:16
	global_load_dwordx4 v[80:83], v6, s[8:9] offset:2048
	global_load_dwordx4 v[84:87], v6, s[8:9] offset:2064
	s_add_i32 s22, s20, 24
	s_lshl_b32 s0, s22, 12
	s_sub_u32 s1, s0, 0x10000000
	s_cmp_lt_u32 s22, 0x10000
	s_cselect_b32 s0, s0, s1
	s_cselect_b32 s24, s16, s18
	s_cselect_b32 s25, s17, s19
	s_add_u32 s8, s24, s0
	s_addc_u32 s9, s25, 0
	global_load_dwordx4 v[88:91], v6, s[8:9]
	global_load_dwordx4 v[92:95], v6, s[8:9] offset:16
	global_load_dwordx4 v[96:99], v6, s[8:9] offset:2048
	global_load_dwordx4 v[100:103], v6, s[8:9] offset:2064
	s_add_i32 s22, s20, 32
	s_lshl_b32 s0, s22, 12
	s_sub_u32 s1, s0, 0x10000000
	s_cmp_lt_u32 s22, 0x10000
	s_cselect_b32 s0, s0, s1
	s_cselect_b32 s24, s16, s18
	s_cselect_b32 s25, s17, s19
	s_add_u32 s8, s24, s0
	s_addc_u32 s9, s25, 0
	global_load_dwordx4 v[104:107], v6, s[8:9]
	global_load_dwordx4 v[108:111], v6, s[8:9] offset:16
	global_load_dwordx4 v[112:115], v6, s[8:9] offset:2048
	global_load_dwordx4 v[116:119], v6, s[8:9] offset:2064
.Lm0_loop:
	s_lshr_b32 s0, s20, 11
	s_cmp_eq_u32 s0, s21
	s_cbranch_scc1 .Lm0_ok0
	s_mov_b32 s1, 0
	s_branch .Lm0_par
.Lm0_ok0:
	s_waitcnt vmcnt(24)
	v_pk_fma_f32 v[40:41], v[40:41], v[8:9], v[24:25]
	v_pk_fma_f32 v[42:43], v[42:43], v[10:11], v[26:27]
	v_pk_fma_f32 v[44:45], v[44:45], v[12:13], v[28:29]
	v_pk_fma_f32 v[46:47], v[46:47], v[14:15], v[30:31]
	v_pk_fma_f32 v[48:49], v[48:49], v[16:17], v[32:33]
	v_pk_fma_f32 v[50:51], v[50:51], v[18:19], v[34:35]
	v_pk_fma_f32 v[52:53], v[52:53], v[20:21], v[36:37]
	v_pk_fma_f32 v[54:55], v[54:55], v[22:23], v[38:39]
	s_nop 0
	v_cvt_pk_bf16_f32 v120, v40, v41
	v_cvt_pk_bf16_f32 v121, v42, v43
	v_cvt_pk_bf16_f32 v122, v44, v45
	v_cvt_pk_bf16_f32 v123, v46, v47
	v_cvt_pk_bf16_f32 v124, v48, v49
	v_cvt_pk_bf16_f32 v125, v50, v51
	v_cvt_pk_bf16_f32 v126, v52, v53
	v_cvt_pk_bf16_f32 v127, v54, v55
	s_lshl_b32 s0, s20, 11
	s_add_u32 s8, s10, s0
	s_addc_u32 s9, s11, 0
	s_add_i32 s22, s20, 40
	s_cmp_lt_u32 s22, s7
	s_cselect_b32 s22, s22, s20
	global_store_dwordx4 v1, v[120:123], s[8:9]
	global_store_dwordx4 v1, v[124:127], s[8:9] offset:1024
	s_lshl_b32 s0, s22, 12
	s_sub_u32 s1, s0, 0x10000000
	s_cmp_lt_u32 s22, 0x10000
	s_cselect_b32 s0, s0, s1
	s_cselect_b32 s24, s16, s18
	s_cselect_b32 s25, s17, s19
	s_add_u32 s8, s24, s0
	s_addc_u32 s9, s25, 0
	global_load_dwordx4 v[40:43], v6, s[8:9]
	global_load_dwordx4 v[44:47], v6, s[8:9] offset:16
	global_load_dwordx4 v[48:51], v6, s[8:9] offset:2048
	global_load_dwordx4 v[52:55], v6, s[8:9] offset:2064
	s_add_i32 s23, s20, 8
	s_lshr_b32 s0, s23, 11
	s_cmp_eq_u32 s0, s21
	s_cbranch_scc1 .Lm0_ok1
	s_mov_b32 s1, 1
	s_branch .Lm0_par
.Lm0_ok1:
	s_waitcnt vmcnt(24)
	v_pk_fma_f32 v[56:57], v[56:57], v[8:9], v[24:25]
	v_pk_fma_f32 v[58:59], v[58:59], v[10:11], v[26:27]
	v_pk_fma_f32 v[60:61], v[60:61], v[12:13], v[28:29]
	v_pk_fma_f32 v[62:63], v[62:63], v[14:15], v[30:31]
	v_pk_fma_f32 v[64:65], v[64:65], v[16:17], v[32:33]
	v_pk_fma_f32 v[66:67], v[66:67], v[18:19], v[34:35]
	v_pk_fma_f32 v[68:69], v[68:69], v[20:21], v[36:37]
	v_pk_fma_f32 v[70:71], v[70:71], v[22:23], v[38:39]
	s_nop 0
	v_cvt_pk_bf16_f32 v120, v56, v57
	v_cvt_pk_bf16_f32 v121, v58, v59
	v_cvt_pk_bf16_f32 v122, v60, v61
	v_cvt_pk_bf16_f32 v123, v62, v63
	v_cvt_pk_bf16_f32 v124, v64, v65
	v_cvt_pk_bf16_f32 v125, v66, v67
	v_cvt_pk_bf16_f32 v126, v68, v69
	v_cvt_pk_bf16_f32 v127, v70, v71
	s_lshl_b32 s0, s23, 11
	s_add_u32 s8, s10, s0
	s_addc_u32 s9, s11, 0
	s_add_i32 s22, s23, 40
	s_cmp_lt_u32 s22, s7
	s_cselect_b32 s22, s22, s23
	global_store_dwordx4 v1, v[120:123], s[8:9]
	global_store_dwordx4 v1, v[124:127], s[8:9] offset:1024
	s_lshl_b32 s0, s22, 12
	s_sub_u32 s1, s0, 0x10000000
	s_cmp_lt_u32 s22, 0x10000
	s_cselect_b32 s0, s0, s1
	s_cselect_b32 s24, s16, s18
	s_cselect_b32 s25, s17, s19
	s_add_u32 s8, s24, s0
	s_addc_u32 s9, s25, 0
	global_load_dwordx4 v[56:59], v6, s[8:9]
	global_load_dwordx4 v[60:63], v6, s[8:9] offset:16
	global_load_dwordx4 v[64:67], v6, s[8:9] offset:2048
	global_load_dwordx4 v[68:71], v6, s[8:9] offset:2064
	s_add_i32 s23, s20, 16
	s_lshr_b32 s0, s23, 11
	s_cmp_eq_u32 s0, s21
	s_cbranch_scc1 .Lm0_ok2
	s_mov_b32 s1, 2
	s_branch .Lm0_par
; __device__ void phase_modulate0(PP P, int wid) {
;     ...
;     for (size_t it = (size_t)blockIdx.x * NTHREADS + tidx; it < (size_t)MT * 128; it += (size_t)gridDim.x * NTHREADS) {
;         const int token = (int)(it >> 7), c8 = (int)(it & 127) * 8, seq = token >> 11;
;         float x[8], sh[8], sc[8], u[8];
;         load8f(xin_row(P, token) + c8, x);
;         const float* mrow = mod + (size_t)(0 * NSEQ + seq) * 6 * D;
;         load8f(mrow + c8, sh); load8f(mrow + D + c8, sc);
; #pragma unroll
;         for (int e = 0; e < 8; ++e) u[e] = x[e] * (1.f + sc[e]) + sh[e];
;         store_A(A, false, token, c8, u);
;     }
.Lm0_ok2:
	s_waitcnt vmcnt(24)
	v_pk_fma_f32 v[72:73], v[72:73], v[8:9], v[24:25]
	v_pk_fma_f32 v[74:75], v[74:75], v[10:11], v[26:27]
	v_pk_fma_f32 v[76:77], v[76:77], v[12:13], v[28:29]
	v_pk_fma_f32 v[78:79], v[78:79], v[14:15], v[30:31]
	v_pk_fma_f32 v[80:81], v[80:81], v[16:17], v[32:33]
	v_pk_fma_f32 v[82:83], v[82:83], v[18:19], v[34:35]
	v_pk_fma_f32 v[84:85], v[84:85], v[20:21], v[36:37]
	v_pk_fma_f32 v[86:87], v[86:87], v[22:23], v[38:39]
	s_nop 0
	v_cvt_pk_bf16_f32 v120, v72, v73
	v_cvt_pk_bf16_f32 v121, v74, v75
	v_cvt_pk_bf16_f32 v122, v76, v77
	v_cvt_pk_bf16_f32 v123, v78, v79
	v_cvt_pk_bf16_f32 v124, v80, v81
	v_cvt_pk_bf16_f32 v125, v82, v83
	v_cvt_pk_bf16_f32 v126, v84, v85
	v_cvt_pk_bf16_f32 v127, v86, v87
	s_lshl_b32 s0, s23, 11
	s_add_u32 s8, s10, s0
	s_addc_u32 s9, s11, 0
	s_add_i32 s22, s23, 40
	s_cmp_lt_u32 s22, s7
	s_cselect_b32 s22, s22, s23
	global_store_dwordx4 v1, v[120:123], s[8:9]
	global_store_dwordx4 v1, v[124:127], s[8:9] offset:1024
	s_lshl_b32 s0, s22, 12
	s_sub_u32 s1, s0, 0x10000000
	s_cmp_lt_u32 s22, 0x10000
	s_cselect_b32 s0, s0, s1
	s_cselect_b32 s24, s16, s18
	s_cselect_b32 s25, s17, s19
	s_add_u32 s8, s24, s0
	s_addc_u32 s9, s25, 0
	global_load_dwordx4 v[72:75], v6, s[8:9]
	global_load_dwordx4 v[76:79], v6, s[8:9] offset:16
	global_load_dwordx4 v[80:83], v6, s[8:9] offset:2048
	global_load_dwordx4 v[84:87], v6, s[8:9] offset:2064
	s_add_i32 s23, s20, 24
	s_lshr_b32 s0, s23, 11
	s_cmp_eq_u32 s0, s21
	s_cbranch_scc1 .Lm0_ok3
	s_mov_b32 s1, 3
	s_branch .Lm0_par
.Lm0_ok3:
	s_waitcnt vmcnt(24)
	v_pk_fma_f32 v[88:89], v[88:89], v[8:9], v[24:25]
	v_pk_fma_f32 v[90:91], v[90:91], v[10:11], v[26:27]
	v_pk_fma_f32 v[92:93], v[92:93], v[12:13], v[28:29]
	v_pk_fma_f32 v[94:95], v[94:95], v[14:15], v[30:31]
	v_pk_fma_f32 v[96:97], v[96:97], v[16:17], v[32:33]
	v_pk_fma_f32 v[98:99], v[98:99], v[18:19], v[34:35]
	v_pk_fma_f32 v[100:101], v[100:101], v[20:21], v[36:37]
	v_pk_fma_f32 v[102:103], v[102:103], v[22:23], v[38:39]
	s_nop 0
	v_cvt_pk_bf16_f32 v120, v88, v89
	v_cvt_pk_bf16_f32 v121, v90, v91
	v_cvt_pk_bf16_f32 v122, v92, v93
	v_cvt_pk_bf16_f32 v123, v94, v95
	v_cvt_pk_bf16_f32 v124, v96, v97
	v_cvt_pk_bf16_f32 v125, v98, v99
	v_cvt_pk_bf16_f32 v126, v100, v101
	v_cvt_pk_bf16_f32 v127, v102, v103
	s_lshl_b32 s0, s23, 11
	s_add_u32 s8, s10, s0
	s_addc_u32 s9, s11, 0
	s_add_i32 s22, s23, 40
	s_cmp_lt_u32 s22, s7
	s_cselect_b32 s22, s22, s23
	global_store_dwordx4 v1, v[120:123], s[8:9]
	global_store_dwordx4 v1, v[124:127], s[8:9] offset:1024
	s_lshl_b32 s0, s22, 12
	s_sub_u32 s1, s0, 0x10000000
	s_cmp_lt_u32 s22, 0x10000
	s_cselect_b32 s0, s0, s1
	s_cselect_b32 s24, s16, s18
	s_cselect_b32 s25, s17, s19
	s_add_u32 s8, s24, s0
	s_addc_u32 s9, s25, 0
	global_load_dwordx4 v[88:91], v6, s[8:9]
	global_load_dwordx4 v[92:95], v6, s[8:9] offset:16
	global_load_dwordx4 v[96:99], v6, s[8:9] offset:2048
	global_load_dwordx4 v[100:103], v6, s[8:9] offset:2064
	s_add_i32 s23, s20, 32
	s_lshr_b32 s0, s23, 11
	s_cmp_eq_u32 s0, s21
	s_cbranch_scc1 .Lm0_ok4
	s_mov_b32 s1, 4
	s_branch .Lm0_par
.Lm0_ok4:
	s_waitcnt vmcnt(24)
	v_pk_fma_f32 v[104:105], v[104:105], v[8:9], v[24:25]
	v_pk_fma_f32 v[106:107], v[106:107], v[10:11], v[26:27]
	v_pk_fma_f32 v[108:109], v[108:109], v[12:13], v[28:29]
	v_pk_fma_f32 v[110:111], v[110:111], v[14:15], v[30:31]
	v_pk_fma_f32 v[112:113], v[112:113], v[16:17], v[32:33]
	v_pk_fma_f32 v[114:115], v[114:115], v[18:19], v[34:35]
	v_pk_fma_f32 v[116:117], v[116:117], v[20:21], v[36:37]
	v_pk_fma_f32 v[118:119], v[118:119], v[22:23], v[38:39]
	s_nop 0
	v_cvt_pk_bf16_f32 v120, v104, v105
	v_cvt_pk_bf16_f32 v121, v106, v107
	v_cvt_pk_bf16_f32 v122, v108, v109
	v_cvt_pk_bf16_f32 v123, v110, v111
	v_cvt_pk_bf16_f32 v124, v112, v113
	v_cvt_pk_bf16_f32 v125, v114, v115
	v_cvt_pk_bf16_f32 v126, v116, v117
	v_cvt_pk_bf16_f32 v127, v118, v119
	s_lshl_b32 s0, s23, 11
	s_add_u32 s8, s10, s0
	s_addc_u32 s9, s11, 0
	s_add_i32 s22, s23, 40
	s_cmp_lt_u32 s22, s7
	s_cselect_b32 s22, s22, s23
	global_store_dwordx4 v1, v[120:123], s[8:9]
	global_store_dwordx4 v1, v[124:127], s[8:9] offset:1024
	s_lshl_b32 s0, s22, 12
	s_sub_u32 s1, s0, 0x10000000
	s_cmp_lt_u32 s22, 0x10000
	s_cselect_b32 s0, s0, s1
	s_cselect_b32 s24, s16, s18
	s_cselect_b32 s25, s17, s19
	s_add_u32 s8, s24, s0
	s_addc_u32 s9, s25, 0
	global_load_dwordx4 v[104:107], v6, s[8:9]
	global_load_dwordx4 v[108:111], v6, s[8:9] offset:16
	global_load_dwordx4 v[112:115], v6, s[8:9] offset:2048
	global_load_dwordx4 v[116:119], v6, s[8:9] offset:2064
	s_add_i32 s20, s20, 40
	s_cmp_lt_u32 s20, s7
	s_cbranch_scc1 .Lm0_loop
	s_branch .Lm0_done
.Lm0_par:
	s_mov_b32 s21, s0
	s_mul_i32 s0, s0, 0x6000
	s_add_u32 s8, s12, s0
	s_addc_u32 s9, s13, 0
	s_add_u32 s24, s8, 0x1000
	s_addc_u32 s25, s9, 0
	global_load_dwordx4 v[24:27], v6, s[8:9]
	global_load_dwordx4 v[28:31], v6, s[8:9] offset:16
	global_load_dwordx4 v[32:35], v6, s[8:9] offset:2048
	global_load_dwordx4 v[36:39], v6, s[8:9] offset:2064
	global_load_dwordx4 v[8:11], v6, s[24:25]
	global_load_dwordx4 v[12:15], v6, s[24:25] offset:16
	global_load_dwordx4 v[16:19], v6, s[24:25] offset:2048
	global_load_dwordx4 v[20:23], v6, s[24:25] offset:2064
	s_waitcnt vmcnt(0)
	v_pk_add_f32 v[8:9], v[8:9], 1.0 op_sel_hi:[1,0]
	v_pk_add_f32 v[10:11], v[10:11], 1.0 op_sel_hi:[1,0]
	v_pk_add_f32 v[12:13], v[12:13], 1.0 op_sel_hi:[1,0]
	v_pk_add_f32 v[14:15], v[14:15], 1.0 op_sel_hi:[1,0]
	v_pk_add_f32 v[16:17], v[16:17], 1.0 op_sel_hi:[1,0]
	v_pk_add_f32 v[18:19], v[18:19], 1.0 op_sel_hi:[1,0]
	v_pk_add_f32 v[20:21], v[20:21], 1.0 op_sel_hi:[1,0]
	v_pk_add_f32 v[22:23], v[22:23], 1.0 op_sel_hi:[1,0]
	s_nop 1
	s_cmp_eq_u32 s1, 0
	s_cbranch_scc1 .Lm0_ok0
	s_cmp_eq_u32 s1, 1
	s_cbranch_scc1 .Lm0_ok1
	s_cmp_eq_u32 s1, 2
	s_cbranch_scc1 .Lm0_ok2
	s_cmp_eq_u32 s1, 3
	s_cbranch_scc1 .Lm0_ok3
	s_branch .Lm0_ok4
.Lm0_done:
	s_mov_b64 s[8:9], exec
	s_branch .LBB0_110
.Lm0_orig:
	v_mbcnt_lo_u32_b32 v0, -1, 0
	v_mbcnt_hi_u32_b32 v0, -1, v0
	s_mov_b64 s[0:1], 0xa00000
	v_add_u32_e32 v2, s82, v0
	v_ashrrev_i32_e32 v3, 31, v2
	v_lshl_add_u64 v[0:1], s[8:9], 0, v[2:3]
	v_cmp_gt_u64_e32 vcc, s[0:1], v[0:1]
	s_and_saveexec_b64 s[8:9], vcc
	s_cbranch_execz .LBB0_110
	s_waitcnt lgkmcnt(0)
	s_add_u32 s20, s6, 0xe200000
	s_addc_u32 s21, s7, 0
	s_add_u32 s6, s6, 0xe660000
	s_addc_u32 s7, s7, 0
	s_mov_b32 s1, 0
	s_mov_b32 s0, s14
	s_lshl_b64 s[12:13], s[2:3], 12
	s_lshl_b64 s[10:11], s[0:1], 9
	v_lshl_add_u64 v[2:3], v[2:3], 3, s[12:13]
	s_lshl_b64 s[12:13], s[0:1], 12
	s_mov_b64 s[16:17], 0
	s_mov_b64 s[18:19], 0x800000
	v_mov_b32_e32 v5, 0
	s_movk_i32 s0, 0x6000
	v_mov_b64_e32 v[6:7], s[20:21]
	s_mov_b64 s[20:21], 0x1000
	s_movk_i32 s1, 0x1000
	s_mov_b64 s[22:23], 0x9fffff
